# v108 + static s_setprio 1 for waves 4-7 in the conv/prep FOR_ITEMS phase too (mixer phase stays at priority 0)
# baseline (speedup 1.0000x reference)
.LBB0_361:
	s_or_b64 exec, exec, s[0:1]
	s_waitcnt lgkmcnt(0)
	s_setprio 0
	s_barrier
	ds_read_b32 v0, v230
	v_readfirstlane_b32 s0, v195
	s_cmpk_lt_u32 s0, 0x100
	s_cbranch_scc1 .Lprio_prep
	s_setprio 1
.Lprio_prep:
	s_movk_i32 s0, 0x5ff
	s_waitcnt lgkmcnt(0)
	v_cmp_lt_i32_e64 s[0:1], s0, v0
	s_nop 1
	v_writelane_b32 v254, s0, 54
	v_lshl_add_u32 v4, v0, 1, v216
	v_cmp_gt_i32_e32 vcc, s21, v4
	v_writelane_b32 v254, s1, 55
	v_readfirstlane_b32 s0, v0
	s_cmpk_lt_i32 s0, 0x600
	s_cselect_b64 s[0:1], -1, 0
	s_and_b64 s[0:1], s[0:1], vcc
	s_and_saveexec_b64 s[92:93], s[0:1]
	s_cbranch_execz .LBB0_356
	v_add_u32_e32 v0, 0xfffff600, v4
	s_movk_i32 s0, 0xf6ff
	v_cmp_lt_u32_e32 vcc, s0, v0
	s_movk_i32 s0, 0xa00
	v_cmp_gt_i32_e64 s[0:1], s0, v4
	v_mov_b32_e32 v0, 0xfffff700
	s_nop 0
	v_cndmask_b32_e64 v0, v0, v236, s[0:1]
	v_add_u32_e32 v5, v0, v4
	s_and_saveexec_b64 s[0:1], vcc
	s_xor_b64 s[60:61], exec, s[0:1]
	s_cbranch_execz .LBB0_434
	s_movk_i32 s0, 0x7ff
	v_cmp_lt_i32_e32 vcc, s0, v5
	s_and_saveexec_b64 s[0:1], vcc
	s_xor_b64 s[0:1], exec, s[0:1]
	s_cbranch_execz .LBB0_380
	v_mov_b32_e32 v0, v217
	s_nop 0
	v_cmp_eq_u32_e32 vcc, 0, v0
	s_and_saveexec_b64 s[42:43], vcc
	ds_write_b32 v227, v17
	s_or_b64 exec, exec, s[42:43]
	v_add_u32_e32 v1, 0xfffff800, v5
	s_waitcnt vmcnt(1)
	v_lshlrev_b32_e32 v2, 4, v5
	v_lshrrev_b32_e32 v1, 4, v1
	v_and_b32_e32 v4, 3, v4
	v_and_b32_e32 v2, 0xc0, v2
	v_lshl_or_b32 v16, v1, 2, v4
	v_lshl_or_b32 v1, v1, 8, v2
	v_mov_b64_e32 v[2:3], s[30:31]
	v_mad_u64_u32 v[2:3], s[40:41], v1, s33, v[2:3]
	v_lshlrev_b32_e32 v4, 8, v4
	v_mov_b32_e32 v5, v17
	v_readlane_b32 s40, v254, 31
	v_lshl_add_u64 v[2:3], v[2:3], 0, v[4:5]
	v_lshlrev_b64 v[4:5], 16, v[16:17]
	v_readlane_b32 s41, v254, 32
	v_ashrrev_i32_e32 v100, 2, v0
	v_lshlrev_b32_e32 v14, 5, v0
	v_lshl_add_u64 v[6:7], s[40:41], 0, v[4:5]
	v_readlane_b32 s40, v254, 29
	v_ashrrev_i32_e32 v8, 1, v0
	v_ashrrev_i32_e32 v101, 31, v100
	v_and_b32_e32 v9, 0x60, v14
	v_readlane_b32 s41, v254, 30
	v_bfi_b32 v1, -16, v100, v0
	v_lshlrev_b64 v[10:11], 8, v[100:101]
	v_lshlrev_b32_e32 v102, 1, v9
	v_ashrrev_i32_e32 v9, 31, v8
	v_lshl_add_u64 v[4:5], s[40:41], 0, v[4:5]
	v_lshl_add_u64 v[10:11], v[6:7], 0, v[10:11]
	v_mov_b32_e32 v103, v17
	v_lshlrev_b64 v[12:13], 9, v[8:9]
	v_and_b32_e32 v9, 32, v14
	v_mad_i64_i32 v[108:109], s[40:41], v1, s33, v[2:3]
	v_and_b32_e32 v16, 48, v0
	v_lshl_add_u64 v[10:11], v[10:11], 0, v[102:103]
	v_lshl_add_u64 v[4:5], v[4:5], 0, v[12:13]
	v_lshlrev_b32_e32 v104, 1, v9
	v_mov_b32_e32 v105, v17
	v_lshl_add_u64 v[2:3], v[108:109], 0, v[16:17]
	v_lshl_add_u64 v[106:107], v[4:5], 0, v[104:105]
	global_load_dwordx4 v[24:27], v[10:11], off
	global_load_dwordx4 v[40:43], v[10:11], off offset:16
	global_load_dwordx4 v[48:51], v[106:107], off
	global_load_dwordx4 v[52:55], v[106:107], off offset:16
	global_load_dwordx4 v[60:63], v[10:11], off offset:32
	global_load_dwordx4 v[64:67], v[10:11], off offset:48
	global_load_dwordx4 v[68:71], v[106:107], off offset:32
	global_load_dwordx4 v[72:75], v[106:107], off offset:48
	global_load_dwordx4 v[28:31], v[2:3], off offset:3072
	global_load_dwordx4 v[32:35], v[2:3], off offset:3136
	global_load_dwordx4 v[36:39], v[2:3], off offset:3200
	global_load_dwordx4 v[44:47], v[2:3], off offset:3264
	v_and_b32_e32 v1, 63, v0
	v_and_b32_e32 v2, 15, v0
	v_bfe_u32 v0, v0, 4, 2
	s_movk_i32 s34, 0x88
	v_lshlrev_b32_e32 v110, 3, v0
	v_mul_lo_u32 v0, v100, s34
	s_movk_i32 s34, 0x44
	v_mul_lo_u32 v3, v8, s34
	v_mul_u32_u24_e32 v4, 0x88, v2
	s_movk_i32 s34, 0x4400
	v_lshlrev_b32_e32 v101, 1, v0
	v_lshlrev_b32_e32 v105, 1, v3
	v_add3_u32 v111, v4, v110, s34
	s_movk_i32 s34, 0x110
	v_mov_b32_e32 v18, v17
	v_mov_b32_e32 v19, v17
	v_add3_u32 v4, v194, v101, v102
	v_add3_u32 v5, v194, v105, v104
	v_mad_u32_u24 v114, v2, s34, v16
	v_mov_b32_e32 v16, v17
	v_cmp_eq_u32_e64 s[42:43], 0, v1
	v_lshl_add_u64 v[112:113], v[6:7], 0, v[102:103]
	v_mov_b64_e32 v[0:1], v[16:17]
	v_mov_b64_e32 v[8:9], v[16:17]
	v_mov_b64_e32 v[22:23], v[18:19]
	v_mov_b64_e32 v[58:59], v[18:19]
	v_mov_b64_e32 v[78:79], v[18:19]
	v_mov_b64_e32 v[82:83], v[18:19]
	v_mov_b64_e32 v[12:13], v[16:17]
	s_mov_b32 s46, 0
	v_mov_b32_e32 v117, 0xff800000
	v_mov_b32_e32 v115, 0
	v_mov_b64_e32 v[2:3], v[18:19]
	v_mov_b64_e32 v[10:11], v[18:19]
	v_mov_b64_e32 v[20:21], v[16:17]
	v_mov_b64_e32 v[56:57], v[16:17]
	v_mov_b64_e32 v[76:77], v[16:17]
	v_mov_b64_e32 v[80:81], v[16:17]
	v_mov_b64_e32 v[14:15], v[18:19]
	s_mov_b32 s48, 0
	s_waitcnt vmcnt(11)
	ds_write_b128 v4, v[24:27]
	s_waitcnt vmcnt(9)
	ds_write_b64 v5, v[48:49] offset:17408
	ds_write_b64 v5, v[50:51] offset:17416
	ds_write_b128 v4, v[40:43] offset:16
	s_waitcnt vmcnt(8)
	ds_write_b64 v5, v[52:53] offset:17424
	ds_write_b64 v5, v[54:55] offset:17432
	s_waitcnt vmcnt(7)
	ds_write_b128 v4, v[60:63] offset:32
	s_waitcnt vmcnt(5)
	ds_write_b64 v5, v[68:69] offset:17440
	ds_write_b64 v5, v[70:71] offset:17448
	ds_write_b128 v4, v[64:67] offset:48
	s_waitcnt vmcnt(4)
	ds_write_b64 v5, v[72:73] offset:17456
	ds_write_b64 v5, v[74:75] offset:17464
	v_mov_b64_e32 v[4:5], v[16:17]
	v_mov_b64_e32 v[6:7], v[18:19]
	s_waitcnt lgkmcnt(0)
	s_barrier

.LBB0_678:
	s_or_b64 exec, exec, s[0:1]
	s_waitcnt lgkmcnt(0)
	s_setprio 0
	s_barrier
	ds_read_b32 v0, v230
	s_movk_i32 s0, 0x3bf
	s_movk_i32 s25, 0x780
	s_waitcnt lgkmcnt(0)
	v_cmp_lt_i32_e64 s[40:41], s0, v0
	v_readfirstlane_b32 s0, v0
	v_lshl_add_u32 v4, v0, 1, v216
	s_cmpk_lt_i32 s0, 0x3c0
	s_cselect_b64 s[0:1], -1, 0
	v_cmp_gt_i32_e32 vcc, s25, v4
	s_and_b64 s[0:1], s[0:1], vcc
	s_and_saveexec_b64 s[84:85], s[0:1]
	s_cbranch_execz .LBB0_673
	v_add_u32_e32 v0, 0xfffffa80, v4
	s_movk_i32 s0, 0xfb7f
	v_cmp_lt_u32_e32 vcc, s0, v0
	s_movk_i32 s0, 0x580
	v_cmp_gt_i32_e64 s[0:1], s0, v4
	v_mov_b32_e32 v0, 0xfffffb80
	s_nop 0
	v_cndmask_b32_e64 v0, v0, v236, s[0:1]
	v_add_u32_e32 v5, v0, v4
	s_and_saveexec_b64 s[0:1], vcc
	s_xor_b64 s[0:1], exec, s[0:1]
	s_cbranch_execz .LBB0_685
	s_movk_i32 s25, 0x3ff
	v_cmp_lt_i32_e32 vcc, s25, v5
	s_mov_b64 s[46:47], 0
	s_and_saveexec_b64 s[42:43], vcc
	s_xor_b64 s[44:45], exec, s[42:43]
	s_cbranch_execnz .LBB0_770
	s_andn2_saveexec_b64 s[44:45], s[44:45]
	s_cbranch_execnz .LBB0_790
